# grid barrier poll sleeps shortened (8->2, 4->1)
# baseline (speedup 1.0000x reference)
.LBB0_71:
	s_sleep 2
	global_load_dword v4, v3, s[6:7] sc1
	s_waitcnt vmcnt(0)
	v_cmp_ge_u32_e64 s[0:1], v4, v2
	s_or_b64 s[8:9], s[0:1], s[8:9]
	s_andn2_b64 exec, exec, s[8:9]
	s_cbranch_execnz .LBB0_71

.LBB0_77:
	s_sleep 1
	flat_load_dword v4, v[2:3] sc0 sc1
	s_waitcnt vmcnt(0) lgkmcnt(0)
	v_cmp_ne_u32_e32 vcc, 0, v4
	s_or_b64 s[4:5], vcc, s[4:5]
	s_andn2_b64 exec, exec, s[4:5]
	s_cbranch_execnz .LBB0_77

.LBB0_108:
	s_sleep 2
	global_load_dword v3, v195, s[14:15] sc1
	s_waitcnt vmcnt(0)
	v_cmp_ge_u32_e64 s[0:1], v3, v2
	s_or_b64 s[8:9], s[0:1], s[8:9]
	s_andn2_b64 exec, exec, s[8:9]
	s_cbranch_execnz .LBB0_108

.LBB0_114:
	s_sleep 1
	flat_load_dword v2, v[204:205] sc0 sc1
	s_waitcnt vmcnt(0) lgkmcnt(0)
	v_cmp_le_u32_e32 vcc, s4, v2
	s_or_b64 s[6:7], vcc, s[6:7]
	s_andn2_b64 exec, exec, s[6:7]
	s_cbranch_execnz .LBB0_114

.LBB0_350:
	s_sleep 2
	global_load_dword v3, v195, s[14:15] sc1
	s_waitcnt vmcnt(0)
	v_cmp_ge_u32_e64 s[4:5], v3, v2
	s_or_b64 s[6:7], s[4:5], s[6:7]
	s_andn2_b64 exec, exec, s[6:7]
	s_cbranch_execnz .LBB0_350

.LBB0_356:
	s_sleep 1
	flat_load_dword v2, v[204:205] sc0 sc1
	s_waitcnt vmcnt(0) lgkmcnt(0)
	v_cmp_le_u32_e32 vcc, s10, v2
	s_or_b64 s[4:5], vcc, s[4:5]
	s_andn2_b64 exec, exec, s[4:5]
	s_cbranch_execnz .LBB0_356

.LBB0_490:
	s_sleep 2
	global_load_dword v3, v195, s[14:15] sc1
	s_waitcnt vmcnt(0)
	v_cmp_ge_u32_e64 s[6:7], v3, v2
	s_or_b64 s[8:9], s[6:7], s[8:9]
	s_andn2_b64 exec, exec, s[8:9]
	s_cbranch_execnz .LBB0_490

.LBB0_529:
	s_sleep 2
	global_load_dword v3, v195, s[14:15] sc1
	s_waitcnt vmcnt(0)
	v_cmp_ge_u32_e64 s[0:1], v3, v2
	s_or_b64 s[6:7], s[0:1], s[6:7]
	s_andn2_b64 exec, exec, s[6:7]
	s_cbranch_execnz .LBB0_529

.LBB0_535:
	s_sleep 1
	flat_load_dword v2, v[204:205] sc0 sc1
	s_waitcnt vmcnt(0) lgkmcnt(0)
	v_cmp_lt_u32_e32 vcc, 6, v2
	s_or_b64 s[4:5], vcc, s[4:5]
	s_andn2_b64 exec, exec, s[4:5]
	s_cbranch_execnz .LBB0_535
	s_branch .LBB0_79
